# rstd table by waves 0-3 only + hand-scheduled PLE epilogue using the LDS table (no 32-load rstd round trip in PLE)
# speedup vs baseline: 1.0086x; 1.0001x over previous
; __device__ __forceinline__ void epi_rstd(const float* ssq, int row0, int fq, float (&rs)[2][4]) {
;     float part[2][4][4];
; #pragma unroll
;     for (int ai = 0; ai < 2; ++ai)
; #pragma unroll
;         for (int m = 0; m < 4; ++m)
; #pragma unroll
;             for (int j = 0; j < 4; ++j) part[ai][m][j] = ssq[(size_t)(4 * fq + j) * M + row0 + ai * 128 + m * 16];
; #pragma unroll
;     for (int ai = 0; ai < 2; ++ai)
; #pragma unroll
;         for (int m = 0; m < 4; ++m) { float t = (part[ai][m][0] + part[ai][m][1]) + (part[ai][m][2] + part[ai][m][3]); t += __shfl_xor(t, 16); t += __shfl_xor(t, 32); rs[ai][m] = __builtin_amdgcn_rsqf(t * (1.0f / 1024.0f) + EPS); }
.LBB0_256:
	v_readlane_b32 s12, v250, 13
	s_mov_b32 s13, -1
	s_cmp_eq_u32 s12, 0
	s_cbranch_scc1 .Lmy_tab_yes
	s_cmp_eq_u32 s12, 5
	s_cbranch_scc1 .Lmy_tab_yes
	s_cmp_eq_u32 s12, 6
	s_cbranch_scc1 .Lmy_tab_yes
	v_writelane_b32 v250, s13, 41
	s_mov_b32 s12, 0
	s_nop 0
	v_writelane_b32 v250, s12, 42
	s_branch .Lmy_tab_done
.Lmy_tab_yes:
	v_writelane_b32 v250, s95, 41
	v_readfirstlane_b32 s12, v195
	s_nop 0
	s_lshr_b32 s12, s12, 8
	s_cmp_lg_u32 s12, 0
	s_cbranch_scc0 .Lmy_tab_ld
	s_mov_b32 s12, 0
	s_nop 0
	v_writelane_b32 v250, s12, 42
	s_branch .Lmy_tab_done
	s_nop 0
	s_nop 0
	s_nop 0
	s_nop 0
	s_nop 0
	s_nop 0
	s_nop 0
	s_nop 0
	s_nop 0
	s_nop 0
	s_nop 0
	s_nop 0
.Lmy_tab_ld:
	s_mov_b32 s12, 1
	s_nop 0
	v_writelane_b32 v250, s12, 42
	v_readlane_b32 s12, v250, 3
	v_readlane_b32 s13, v250, 4
	v_and_b32_e32 v64, 0xff, v195
	v_lshl_add_u32 v64, s95, 8, v64
	v_lshlrev_b32_e32 v64, 2, v64
	s_nop 3
	global_load_dword v66, v64, s[12:13]
	v_add_u32_e32 v65, 0x10000, v64
	global_load_dword v67, v65, s[12:13]
	v_add_u32_e32 v65, 0x20000, v64
	global_load_dword v68, v65, s[12:13]
	v_add_u32_e32 v65, 0x30000, v64
	global_load_dword v69, v65, s[12:13]
	v_add_u32_e32 v65, 0x40000, v64
	global_load_dword v70, v65, s[12:13]
	v_add_u32_e32 v65, 0x50000, v64
	global_load_dword v71, v65, s[12:13]
	v_add_u32_e32 v65, 0x60000, v64
	global_load_dword v72, v65, s[12:13]
	v_add_u32_e32 v65, 0x70000, v64
	global_load_dword v73, v65, s[12:13]
	v_add_u32_e32 v65, 0x80000, v64
	global_load_dword v74, v65, s[12:13]
	v_add_u32_e32 v65, 0x90000, v64
	global_load_dword v75, v65, s[12:13]
	v_add_u32_e32 v65, 0xa0000, v64
	global_load_dword v76, v65, s[12:13]
	v_add_u32_e32 v65, 0xb0000, v64
	global_load_dword v77, v65, s[12:13]
	v_add_u32_e32 v65, 0xc0000, v64
	global_load_dword v78, v65, s[12:13]
	v_add_u32_e32 v65, 0xd0000, v64
	global_load_dword v79, v65, s[12:13]
	v_add_u32_e32 v65, 0xe0000, v64
	global_load_dword v80, v65, s[12:13]
	v_add_u32_e32 v65, 0xf0000, v64
	global_load_dword v81, v65, s[12:13]
